# the closing s_barrier of the barriers in front of the W_in, W_out, gate/up and down GEMM phases moved down to the first memory access of the phase set-up: seven waves run the cold address set-up while
# speedup vs baseline: 1.0002x; 1.0002x over previous
; __device__ __forceinline__ void xcd_barrier(const XcdBarrier& b) {
;     ...
;     }
;     __syncthreads();
.LBB0_113:
	s_or_b64 exec, exec, s[2:3]
.LBB0_114:
	s_waitcnt lgkmcnt(0)

; #define PG8_STAGE(bufoff, gbase, voff) do { _Pragma("unroll") for (int _i = 0; _i < 2; ++_i) \
;         __builtin_amdgcn_global_load_lds((const unsigned*)((const char*)(gbase) + (voff)[_i]), (PG8_LAS unsigned*)(lds + (bufoff) + ldsw + _i * 8192), 16, 0, 0); } while (0)
; #define PG8_BAR __builtin_amdgcn_s_barrier()
; template <class Epi, class Sched, bool ALIGN_EPI = false, bool SP2 = false>
; __device__ __forceinline__ void gemm_phase(PG8_LAS unsigned char* lds, const Gemm g, const Sched& S, const Epi& E) {
;     int tid_l = threadIdx.x; asm volatile("" : "+v"(tid_l));
;     const int tid = tid_l, wid = __builtin_amdgcn_readfirstlane(tid >> 6), lane = tid & 63, wr = wid >> 2, wc = wid & 3, fr = lane & 15, fq = lane >> 4;
;     const int K = g.K, nt = K / BK;
;     unsigned voffA[2], voffB[2];
; #pragma unroll
;     for (int i = 0; i < 2; ++i) { int R, C; stage_rc(tid * 16 + i * 8192, R, C); const int Rb = Epi::PERM ? ((R & ~31) + perm32(R & 31)) : R;
;         voffA[i] = (unsigned)(R * K + C) * 2u; voffB[i] = (unsigned)(Rb * K + C) * 2u; }
;     const size_t kstep = (size_t)(BK * 2);
;     const size_t hstep = (size_t)HALF * K * 2;
;     const size_t tstep = 2 * hstep;
;     const unsigned ldsw = (unsigned)wid * 1024u;
;     const int aoff = lds_byte(wr * 64 + fr, fq * 8), boff = lds_byte(wc * 32 + fr, fq * 8);
;     ...
;     const char* cA = (const char*)g.A + (size_t)cur.pm * tstep; const char* cB = (const char*)g.Bt + (size_t)cur.pn * tstep;
;     S.a_ready(cur);
;     if constexpr (SP2) {
;         PG8_STAGE(PG8_SB(0, 0), cB, voffB); PG8_STAGE(PG8_SB(0, 1), cB + hstep, voffB); PG8_STAGE(PG8_SA(0, 0), cA, voffA); PG8_STAGE(PG8_SA(0, 1), cA + hstep, voffA);
;         if (wr == 1) PG8_BAR;
.LBB0_166:
	s_andn2_b64 vcc, exec, s[2:3]
	s_cbranch_vccnz .Leb_p1_stub
	v_readlane_b32 s2, v250, 55
	v_mov_b32_e32 v3, v204
	v_readlane_b32 s3, v250, 56
	s_andn2_b64 vcc, exec, s[2:3]
	v_readfirstlane_b32 s2, v3
	s_cbranch_vccnz .Leb_p1_stub
	v_readlane_b32 s100, v250, 59
	v_bfe_u32 v252, v204, 8, 1
	v_and_b32_e32 v253, 15, v204
	v_lshl_or_b32 v252, v252, 6, v253
	v_add_u32_e32 v252, s100, v252
	v_mov_b32_e32 v253, 0
	v_lshl_add_u64 v[252:253], v[252:253], 3, s[4:5]
	v_lshlrev_b32_e32 v1, 4, v3
	v_add_u32_e32 v0, 0x2000, v1
	v_ashrrev_i32_e32 v4, 31, v0
	v_lshrrev_b32_e32 v4, 22, v4
	v_add_u32_e32 v4, v0, v4
	v_ashrrev_i32_e32 v8, 10, v4
	v_mul_i32_i24_e32 v4, 0x400, v8
	v_sub_u32_e32 v0, v0, v4
	v_lshrrev_b32_e32 v4, 4, v0
	v_bitop3_b32 v0, v4, v0, 32 bitop3:0x6c
	v_ashrrev_i32_e32 v4, 31, v0
	v_lshrrev_b32_e32 v4, 26, v4
	v_add_u32_e32 v4, v0, v4
	s_waitcnt lgkmcnt(0)
	v_lshlrev_b32_e32 v5, 3, v8
	v_ashrrev_i32_e32 v9, 6, v4
	v_and_b32_e32 v5, -16, v5
	v_add_u32_e32 v5, v9, v5
	v_and_b32_e32 v6, 3, v9
	s_mov_b32 s6, 0xfffe0
	v_lshrrev_b32_e32 v7, 2, v5
	v_lshlrev_b32_e32 v10, 1, v5
	v_and_b32_e32 v4, 0xc0, v4
	v_and_or_b32 v6, v5, s6, v6
	v_and_b32_e32 v7, 4, v7
	v_and_b32_e32 v10, 24, v10
	v_sub_u32_e32 v0, v0, v4
	v_or3_b32 v6, v6, v7, v10
	v_lshlrev_b32_e32 v7, 5, v8
	v_ashrrev_i16_sdwa v0, v207, sext(v0) dst_sel:DWORD dst_unused:UNUSED_PAD src0_sel:DWORD src1_sel:BYTE_0
	v_and_b32_e32 v7, 32, v7
	v_bfe_i32 v10, v0, 0, 16
	v_add_lshl_u32 v4, v7, v10, 1
	v_lshl_add_u32 v0, v6, 12, v4
	v_lshl_add_u32 v132, v5, 12, v4
	v_bfe_i32 v4, v3, 27, 1
	v_lshrrev_b32_e32 v4, 22, v4
	v_add_u32_e32 v4, v1, v4
	v_and_b32_e32 v4, 0xfffffc00, v4
	v_sub_u32_e32 v1, v1, v4
	v_lshrrev_b32_e32 v4, 4, v1
	v_ashrrev_i32_e32 v5, 31, v3
	v_bitop3_b32 v1, v4, v1, 32 bitop3:0x6c
	v_lshrrev_b32_e32 v5, 26, v5
	v_ashrrev_i32_e32 v4, 31, v1
	v_add_u32_e32 v5, v3, v5
	v_lshrrev_b32_e32 v4, 26, v4
	v_ashrrev_i32_e32 v12, 6, v5
	v_add_u32_e32 v4, v1, v4
	v_lshlrev_b32_e32 v5, 3, v12
	v_ashrrev_i32_e32 v11, 6, v4
	v_and_b32_e32 v5, -16, v5
	v_add_u32_e32 v5, v11, v5
	v_and_b32_e32 v6, 3, v11
	v_lshrrev_b32_e32 v7, 2, v5
	v_lshlrev_b32_e32 v13, 1, v5
	v_and_b32_e32 v4, 0xc0, v4
	s_ashr_i32 s10, s2, 6
	v_and_or_b32 v6, v5, s6, v6
	v_and_b32_e32 v7, 4, v7
	v_and_b32_e32 v13, 24, v13
	v_sub_u32_e32 v1, v1, v4
	s_ashr_i32 s3, s2, 8
	s_lshl_b32 s42, s10, 10
	v_or3_b32 v6, v6, v7, v13
	v_lshlrev_b32_e32 v7, 5, v12
	v_ashrrev_i16_sdwa v1, v207, sext(v1) dst_sel:DWORD dst_unused:UNUSED_PAD src0_sel:DWORD src1_sel:BYTE_0
	v_readlane_b32 s6, v247, 12
	v_and_b32_e32 v7, 32, v7
	v_bfe_i32 v13, v1, 0, 16
	v_readlane_b32 s7, v247, 13
	s_add_u32 s6, s44, s6
	v_add_lshl_u32 v1, v7, v13, 1
	s_addc_u32 s7, s45, s7
	s_add_i32 s43, s42, 0
	v_lshl_add_u32 v134, v6, 12, v1
	s_add_i32 m0, s43, 0x10000
	v_lshl_add_u32 v136, v5, 12, v1
	s_barrier
	global_load_dwordx2 v[172:173], v[252:253], off
	global_load_dwordx2 v[174:175], v[252:253], off offset:128
	global_load_dwordx2 v[176:177], v[252:253], off offset:256
	global_load_dwordx2 v[178:179], v[252:253], off offset:384
	global_load_dwordx2 v[180:181], v[252:253], off offset:1024
	global_load_dwordx2 v[182:183], v[252:253], off offset:1152
	global_load_dwordx2 v[184:185], v[252:253], off offset:1280
	global_load_dwordx2 v[186:187], v[252:253], off offset:1408
	global_load_lds_dwordx4 v134, s[6:7]
	s_add_i32 m0, s43, 0x12000
	s_add_u32 s8, s6, 0x80000
	global_load_lds_dwordx4 v0, s[6:7]
	s_addc_u32 s9, s7, 0
	s_add_i32 m0, s43, 0x14000
	s_add_i32 s46, s43, 0x2000
	global_load_lds_dwordx4 v134, s[8:9]
	s_add_i32 m0, s43, 0x16000
	s_add_i32 s47, s43, 0x4000
	global_load_lds_dwordx4 v0, s[8:9]
	s_mov_b32 m0, s43
	v_readlane_b32 s8, v250, 57
	global_load_lds_dwordx4 v136, s[0:1]
	s_mov_b32 m0, s46
	v_readlane_b32 s9, v250, 58
	global_load_lds_dwordx4 v132, s[0:1]
	s_mov_b32 m0, s47
	s_add_i32 s48, s43, 0x6000
	v_mov_b32_e32 v135, v2
	s_nop 0
	global_load_lds_dwordx4 v136, s[8:9]
	s_mov_b32 m0, s48
	v_mov_b32_e32 v1, v2
	global_load_lds_dwordx4 v132, s[8:9]
	s_cmp_eq_u32 s3, 1
	v_lshl_add_u64 v[4:5], s[6:7], 0, v[134:135]
	s_cselect_b64 s[8:9], -1, 0
	s_cmp_lg_u32 s3, 1
	v_lshl_add_u64 v[6:7], s[6:7], 0, v[0:1]
	s_cbranch_scc1 .LBB0_170
	s_barrier

; #define PG8_WAIT_V(n) asm volatile("s_waitcnt vmcnt(" #n ")" ::: "memory")
; #define PG8_BAR __builtin_amdgcn_s_barrier()
; template <class Epi, class Sched, bool ALIGN_EPI = false, bool SP2 = false>
; __device__ __forceinline__ void gemm_phase(PG8_LAS unsigned char* lds, const Gemm g, const Sched& S, const Epi& E) {
;     ...
;     PG8_WAIT_V(0);
;     if constexpr (!ALIGN_EPI) { if (wr == 0) PG8_BAR; }
;     PG8_BAR;
.LBB0_212:
	s_waitcnt vmcnt(0)
	s_barrier
	s_branch .LBB0_213
.Leb_p1_stub:
	s_barrier

; __device__ __forceinline__ unsigned xb_ld(unsigned* p)              { return __hip_atomic_load(p, __ATOMIC_RELAXED, __HIP_MEMORY_SCOPE_AGENT); }
; __device__ __forceinline__ unsigned xb_add(unsigned* p, unsigned v) { return __hip_atomic_fetch_add(p, v, __ATOMIC_RELAXED, __HIP_MEMORY_SCOPE_AGENT); }
; #define XB_SPIN(cond, bar) do { unsigned _sp = 0; while (cond) { __builtin_amdgcn_s_sleep(1); \
;     if ((++_sp & 255u) == 0u) { if (xb_ld(&(bar)[XB_TMO])) break; if (_sp > XB_SPIN_CAP) { atomicAdd(&(bar)[XB_TMO], 1u); break; } } } } while (0)
; template <class Epi, class Sched, bool ALIGN_EPI = false, bool SP2 = false>
; __device__ __forceinline__ void gemm_phase(PG8_LAS unsigned char* lds, const Gemm g, const Sched& S, const Epi& E) {
;     int tid_l = threadIdx.x; asm volatile("" : "+v"(tid_l));
;     const int tid = tid_l, wid = __builtin_amdgcn_readfirstlane(tid >> 6), lane = tid & 63, wr = wid >> 2, wc = wid & 3, fr = lane & 15, fq = lane >> 4;
;     const int K = g.K, nt = K / BK;
;     unsigned voffA[2], voffB[2];
; #pragma unroll
;     for (int i = 0; i < 2; ++i) { int R, C; stage_rc(tid * 16 + i * 8192, R, C); const int Rb = Epi::PERM ? ((R & ~31) + perm32(R & 31)) : R;
;         voffA[i] = (unsigned)(R * K + C) * 2u; voffB[i] = (unsigned)(Rb * K + C) * 2u; }
;     const size_t kstep = (size_t)(BK * 2);
;     const size_t hstep = (size_t)HALF * K * 2;
;     const size_t tstep = 2 * hstep;
;     const unsigned ldsw = (unsigned)wid * 1024u;
;     const int aoff = lds_byte(wr * 64 + fr, fq * 8), boff = lds_byte(wc * 32 + fr, fq * 8);
; __device__ __forceinline__ void xcc_local_barrier(unsigned* bar, unsigned x, unsigned nloc) {
;     asm volatile("s_waitcnt vmcnt(0)" ::: "memory");
;     __syncthreads();
;     if (threadIdx.x == 0) {
;         __builtin_amdgcn_s_waitcnt(0);
;         const unsigned old = xb_add(&bar[LB_SUB(x)], 1u);
;         const unsigned gen = old / nloc;
;         if (old + 1u == (gen + 1u) * nloc) xb_add(&bar[LB_GEN(x)], 1u);
;         else XB_SPIN(xb_ld(&bar[LB_GEN(x)]) == gen, bar);
;         __builtin_amdgcn_fence(__ATOMIC_ACQUIRE, "agent");
;         asm volatile("s_waitcnt vmcnt(0)" ::: "memory");
;     }
;     __syncthreads();
.LBB0_877:
	s_or_b64 exec, exec, s[2:3]
.LBB0_878:
	s_lshl_b64 s[2:3], s[78:79], 23
	v_readlane_b32 s4, v249, 3
	s_add_u32 s52, s4, s2
	v_readlane_b32 s2, v249, 4
	s_addc_u32 s53, s2, s3
	s_lshl_b32 s76, s78, 13
	s_lshl_b64 s[2:3], s[76:77], 3
	s_add_u32 s2, s80, s2
	v_readlane_b32 s4, v250, 46
	s_addc_u32 s3, s4, s3
	s_add_u32 s4, s2, 0x40000
	s_addc_u32 s5, s3, 0
	s_add_u32 s6, s2, 0x80000
	s_addc_u32 s7, s3, 0
	v_readlane_b32 s10, v250, 10
	s_add_u32 s8, s2, 0xc0000
	v_readlane_b32 s11, v250, 11
	s_addc_u32 s9, s3, 0
	s_mov_b64 s[2:3], -1
	s_and_b64 vcc, exec, s[10:11]
	s_waitcnt lgkmcnt(0)
	s_cbranch_vccz .LBB0_918
	v_readlane_b32 s2, v247, 31
	v_mov_b32_e32 v7, v204
	v_readlane_b32 s3, v247, 32
	s_and_b64 vcc, exec, s[2:3]
	v_readfirstlane_b32 s12, v7
	s_cbranch_vccnz .LBB0_917
	v_lshlrev_b32_e32 v4, 4, v7
	v_add_u32_e32 v1, 0x2000, v4
	v_ashrrev_i32_e32 v0, 31, v1
	v_lshrrev_b32_e32 v0, 22, v0
	v_add_u32_e32 v0, v1, v0
	v_ashrrev_i32_e32 v0, 10, v0
	v_mul_i32_i24_e32 v3, 0x400, v0
	v_sub_u32_e32 v1, v1, v3
	v_lshrrev_b32_e32 v3, 4, v1
	v_bitop3_b32 v3, v3, v1, 32 bitop3:0x6c
	v_ashrrev_i32_e32 v1, 31, v3
	v_lshrrev_b32_e32 v1, 26, v1
	v_add_u32_e32 v5, v3, v1
	v_lshlrev_b32_e32 v6, 3, v0
	v_ashrrev_i32_e32 v1, 6, v5
	v_and_b32_e32 v6, -16, v6
	v_add_u32_e32 v6, v1, v6
	v_and_b32_e32 v8, 3, v1
	s_mov_b32 s2, 0xfffe0
	v_lshrrev_b32_e32 v9, 2, v6
	v_lshlrev_b32_e32 v10, 1, v6
	v_and_b32_e32 v5, 0xc0, v5
	v_and_or_b32 v8, v6, s2, v8
	v_and_b32_e32 v9, 4, v9
	v_and_b32_e32 v10, 24, v10
	v_sub_u32_e32 v3, v3, v5
	v_or3_b32 v8, v8, v9, v10
	v_lshlrev_b32_e32 v9, 5, v0
	v_ashrrev_i16_sdwa v3, v207, sext(v3) dst_sel:DWORD dst_unused:UNUSED_PAD src0_sel:DWORD src1_sel:BYTE_0
	v_and_b32_e32 v9, 32, v9
	v_bfe_i32 v3, v3, 0, 16
	v_add_lshl_u32 v5, v9, v3, 1
	v_lshl_add_u32 v156, v8, 12, v5
	v_lshl_add_u32 v158, v6, 12, v5
	v_bfe_i32 v5, v7, 27, 1
	v_lshrrev_b32_e32 v5, 22, v5
	v_add_u32_e32 v5, v4, v5
	v_and_b32_e32 v5, 0xfffffc00, v5
	v_sub_u32_e32 v4, v4, v5
	v_lshrrev_b32_e32 v5, 4, v4
	v_bitop3_b32 v6, v5, v4, 32 bitop3:0x6c
	v_ashrrev_i32_e32 v5, 31, v7
	v_lshrrev_b32_e32 v5, 26, v5
	v_ashrrev_i32_e32 v4, 31, v6
	v_add_u32_e32 v5, v7, v5
	v_lshrrev_b32_e32 v4, 26, v4
	v_ashrrev_i32_e32 v5, 6, v5
	v_add_u32_e32 v8, v6, v4
	v_lshlrev_b32_e32 v9, 3, v5
	v_ashrrev_i32_e32 v4, 6, v8
	v_and_b32_e32 v9, -16, v9
	v_add_u32_e32 v9, v4, v9
	v_and_b32_e32 v10, 3, v4
	v_lshrrev_b32_e32 v11, 2, v9
	v_lshlrev_b32_e32 v12, 1, v9
	v_and_b32_e32 v8, 0xc0, v8
	s_ashr_i32 s13, s12, 6
	v_and_or_b32 v10, v9, s2, v10
	v_and_b32_e32 v11, 4, v11
	v_and_b32_e32 v12, 24, v12
	v_sub_u32_e32 v6, v6, v8
	s_ashr_i32 s14, s12, 8
	s_lshl_b32 s54, s13, 10
	v_or3_b32 v10, v10, v11, v12
	v_lshlrev_b32_e32 v11, 5, v5
	v_ashrrev_i16_sdwa v6, v207, sext(v6) dst_sel:DWORD dst_unused:UNUSED_PAD src0_sel:DWORD src1_sel:BYTE_0
	v_readlane_b32 s2, v248, 57
	v_and_b32_e32 v11, 32, v11
	v_bfe_i32 v6, v6, 0, 16
	v_readlane_b32 s3, v248, 58
	s_add_u32 s2, s52, s2
	v_add_lshl_u32 v8, v11, v6, 1
	s_addc_u32 s3, s53, s3
	s_add_i32 s55, s54, 0
	v_lshl_add_u32 v172, v10, 12, v8
	s_add_i32 m0, s55, 0x10000
	v_lshl_add_u32 v174, v9, 12, v8
	global_load_lds_dwordx4 v172, s[2:3]
	s_add_i32 m0, s55, 0x12000
	s_add_u32 s10, s2, 0x80000
	global_load_lds_dwordx4 v156, s[2:3]
	s_addc_u32 s11, s3, 0
	s_add_i32 m0, s55, 0x14000
	s_add_i32 s56, s55, 0x2000
	global_load_lds_dwordx4 v172, s[10:11]
	s_add_i32 m0, s55, 0x16000
	s_add_i32 s57, s55, 0x4000
	global_load_lds_dwordx4 v156, s[10:11]
	v_readlane_b32 s10, v248, 62
	s_mov_b32 m0, s55
	v_readlane_b32 s11, v248, 63
	s_add_i32 s58, s55, 0x6000
	s_cmp_eq_u32 s14, 1
	s_nop 2
	global_load_lds_dwordx4 v174, s[10:11]
	s_mov_b32 m0, s56
	s_nop 0
	global_load_lds_dwordx4 v158, s[10:11]
	v_readlane_b32 s10, v247, 0
	s_mov_b32 m0, s57
	v_readlane_b32 s11, v247, 1
	s_nop 4
	global_load_lds_dwordx4 v174, s[10:11]
	s_mov_b32 m0, s58
	s_nop 0
	global_load_lds_dwordx4 v158, s[10:11]
	s_cselect_b64 s[10:11], -1, 0
	s_cmp_lg_u32 s14, 1
	s_cbranch_scc1 .LBB0_882
	s_barrier

; __device__ __forceinline__ float ss_get(const ss_t* p) { const ss_t v = *p; return (float)(unsigned)(v >> 32) + (float)(unsigned)v * 2.3283064365386963e-10f; }
;     __device__ __forceinline__ void mid(f32x4 (&acc)[2][2][4][2], const Unit& u, int wr, int wc, int fr, int fq) const {
;         int row0 = u.pm * BM + wr * 64 + fr; asm volatile("" : "+v"(row0));
; #pragma unroll
;         for (int ai = 0; ai < 2; ++ai)
; #pragma unroll
;             for (int m = 0; m < 4; ++m) { const int row = row0 + ai * HALF + m * 16;
;                 const float ra = 1.0f / sqrtf(ss_get(ssa + row) * (1.0f / 1024.f) + 1e-6f), rbi = sqrtf(ss_get(ssb + row) * (1.0f / 1024.f) + 1e-6f); const float ratio = ra * rbi;
; template <class Epi, class Sched, bool ALIGN_EPI = false, bool SP2 = false>
; __device__ __forceinline__ void gemm_phase(PG8_LAS unsigned char* lds, const Gemm g, const Sched& S, const Epi& E) {
;     int tid_l = threadIdx.x; asm volatile("" : "+v"(tid_l));
;     const int tid = tid_l, wid = __builtin_amdgcn_readfirstlane(tid >> 6), lane = tid & 63, wr = wid >> 2, wc = wid & 3, fr = lane & 15, fq = lane >> 4;
;     const int K = g.K, nt = K / BK;
;     unsigned voffA[2], voffB[2];
; #pragma unroll
;     for (int i = 0; i < 2; ++i) { int R, C; stage_rc(tid * 16 + i * 8192, R, C); const int Rb = Epi::PERM ? ((R & ~31) + perm32(R & 31)) : R;
;         voffA[i] = (unsigned)(R * K + C) * 2u; voffB[i] = (unsigned)(Rb * K + C) * 2u; }
;     const size_t kstep = (size_t)(BK * 2);
;     const size_t hstep = (size_t)HALF * K * 2;
;     const size_t tstep = 2 * hstep;
;     const unsigned ldsw = (unsigned)wid * 1024u;
;     const int aoff = lds_byte(wr * 64 + fr, fq * 8), boff = lds_byte(wc * 32 + fr, fq * 8);
.LBB0_918:
	s_andn2_b64 vcc, exec, s[2:3]
	v_readlane_b32 s2, v248, 19
	v_readlane_b32 s3, v248, 20
	s_nop 1
	v_cndmask_b32_e64 v0, 0, 1, s[2:3]
	v_cmp_ne_u32_e64 s[38:39], 1, v0
	s_cbranch_vccnz .Leb_p3_stub
	v_mov_b32_e32 v11, v204
	s_and_b64 vcc, exec, s[38:39]
	v_readfirstlane_b32 s2, v11
	s_cbranch_vccnz .Leb_p3_stub
	v_readlane_b32 s100, v250, 59
	v_bfe_u32 v252, v204, 8, 1
	v_and_b32_e32 v253, 15, v204
	v_lshl_or_b32 v252, v252, 6, v253
	v_add_u32_e32 v252, s100, v252
	v_mov_b32_e32 v253, 0
	v_lshlrev_b64 v[252:253], 3, v[252:253]
	v_lshl_add_u64 v[98:99], v[252:253], 0, s[6:7]
	v_lshl_add_u64 v[252:253], v[252:253], 0, s[8:9]
	v_lshlrev_b32_e32 v0, 4, v11
	s_waitcnt lgkmcnt(0)
	v_add_u32_e32 v1, 0x2000, v0
	v_ashrrev_i32_e32 v3, 31, v1
	v_lshrrev_b32_e32 v3, 22, v3
	v_add_u32_e32 v3, v1, v3
	v_ashrrev_i32_e32 v3, 10, v3
	v_mul_i32_i24_e32 v4, 0x400, v3
	v_sub_u32_e32 v1, v1, v4
	v_lshrrev_b32_e32 v4, 4, v1
	v_bitop3_b32 v1, v4, v1, 32 bitop3:0x6c
	v_ashrrev_i32_e32 v4, 31, v1
	v_lshrrev_b32_e32 v4, 26, v4
	v_add_u32_e32 v4, v1, v4
	v_lshlrev_b32_e32 v5, 3, v3
	v_ashrrev_i32_e32 v6, 6, v4
	v_and_b32_e32 v5, -16, v5
	v_add_u32_e32 v5, v6, v5
	v_and_b32_e32 v7, 3, v6
	s_mov_b32 s10, 0xfffe0
	v_lshrrev_b32_e32 v8, 2, v5
	v_lshlrev_b32_e32 v9, 1, v5
	v_and_b32_e32 v4, 0xc0, v4
	v_and_or_b32 v7, v5, s10, v7
	v_and_b32_e32 v8, 4, v8
	v_and_b32_e32 v9, 24, v9
	v_sub_u32_e32 v1, v1, v4
	v_or3_b32 v8, v7, v8, v9
	v_lshlrev_b32_e32 v7, 5, v3
	v_ashrrev_i16_sdwa v1, v207, sext(v1) dst_sel:DWORD dst_unused:UNUSED_PAD src0_sel:DWORD src1_sel:BYTE_0
	v_and_b32_e32 v9, 32, v7
	v_bfe_i32 v7, v1, 0, 16
	v_add_lshl_u32 v1, v9, v7, 1
	v_lshl_add_u32 v156, v8, 12, v1
	v_lshl_add_u32 v158, v5, 12, v1
	v_bfe_i32 v1, v11, 27, 1
	v_lshrrev_b32_e32 v1, 22, v1
	v_add_u32_e32 v1, v0, v1
	v_and_b32_e32 v1, 0xfffffc00, v1
	v_sub_u32_e32 v0, v0, v1
	v_lshrrev_b32_e32 v1, 4, v0
	v_ashrrev_i32_e32 v4, 31, v11
	v_bitop3_b32 v0, v1, v0, 32 bitop3:0x6c
	v_lshrrev_b32_e32 v4, 26, v4
	v_ashrrev_i32_e32 v1, 31, v0
	v_add_u32_e32 v4, v11, v4
	v_lshrrev_b32_e32 v1, 26, v1
	v_ashrrev_i32_e32 v9, 6, v4
	v_add_u32_e32 v1, v0, v1
	v_lshlrev_b32_e32 v4, 3, v9
	v_ashrrev_i32_e32 v8, 6, v1
	v_and_b32_e32 v4, -16, v4
	v_add_u32_e32 v4, v8, v4
	v_and_b32_e32 v5, 3, v8
	v_lshrrev_b32_e32 v10, 2, v4
	v_lshlrev_b32_e32 v12, 1, v4
	v_and_b32_e32 v1, 0xc0, v1
	s_ashr_i32 s3, s2, 6
	v_and_or_b32 v5, v4, s10, v5
	v_and_b32_e32 v10, 4, v10
	v_and_b32_e32 v12, 24, v12
	v_sub_u32_e32 v0, v0, v1
	s_ashr_i32 s14, s2, 8
	s_lshl_b32 s50, s3, 10
	v_or3_b32 v5, v5, v10, v12
	v_lshlrev_b32_e32 v10, 5, v9
	v_ashrrev_i16_sdwa v0, v207, sext(v0) dst_sel:DWORD dst_unused:UNUSED_PAD src0_sel:DWORD src1_sel:BYTE_0
	v_readlane_b32 s10, v247, 12
	v_and_b32_e32 v12, 32, v10
	v_bfe_i32 v10, v0, 0, 16
	v_readlane_b32 s11, v247, 13
	s_add_u32 s10, s52, s10
	v_add_lshl_u32 v0, v12, v10, 1
	s_addc_u32 s11, s53, s11
	s_add_i32 s51, s50, 0
	v_lshl_add_u32 v172, v5, 12, v0
	s_add_i32 m0, s51, 0x10000
	v_lshl_add_u32 v174, v4, 12, v0
	s_barrier
	global_load_dwordx2 v[100:101], v[98:99], off
	global_load_dwordx2 v[102:103], v[98:99], off offset:128
	global_load_dwordx2 v[104:105], v[98:99], off offset:256
	global_load_dwordx2 v[106:107], v[98:99], off offset:384
	global_load_dwordx2 v[108:109], v[98:99], off offset:1024
	global_load_dwordx2 v[110:111], v[98:99], off offset:1152
	global_load_dwordx2 v[112:113], v[98:99], off offset:1280
	global_load_dwordx2 v[114:115], v[98:99], off offset:1408
	global_load_dwordx2 v[116:117], v[252:253], off
	global_load_dwordx2 v[118:119], v[252:253], off offset:128
	global_load_dwordx2 v[120:121], v[252:253], off offset:256
	global_load_dwordx2 v[122:123], v[252:253], off offset:384
	global_load_dwordx2 v[124:125], v[252:253], off offset:1024
	global_load_dwordx2 v[126:127], v[252:253], off offset:1152
	global_load_dwordx2 v[128:129], v[252:253], off offset:1280
	global_load_dwordx2 v[130:131], v[252:253], off offset:1408
	global_load_lds_dwordx4 v172, s[10:11]
	s_add_i32 m0, s51, 0x12000
	s_add_u32 s12, s10, 0x80000
	global_load_lds_dwordx4 v156, s[10:11]
	s_addc_u32 s13, s11, 0
	s_add_i32 m0, s51, 0x14000
	s_add_i32 s54, s51, 0x2000
	global_load_lds_dwordx4 v172, s[12:13]
	s_add_i32 m0, s51, 0x16000
	s_add_i32 s55, s51, 0x4000
	global_load_lds_dwordx4 v156, s[12:13]
	s_mov_b32 m0, s51
	v_readlane_b32 s12, v248, 21
	global_load_lds_dwordx4 v174, s[88:89]
	s_mov_b32 m0, s54
	v_readlane_b32 s13, v248, 22
	global_load_lds_dwordx4 v158, s[88:89]
	s_mov_b32 m0, s55
	s_add_i32 s56, s51, 0x6000
	v_mov_b32_e32 v173, v2
	s_nop 0
	global_load_lds_dwordx4 v174, s[12:13]
	s_mov_b32 m0, s56
	v_mov_b32_e32 v157, v2
	global_load_lds_dwordx4 v158, s[12:13]
	s_cmp_eq_u32 s14, 1
	v_lshl_add_u64 v[0:1], s[10:11], 0, v[172:173]
	s_cselect_b64 s[12:13], -1, 0
	s_cmp_lg_u32 s14, 1
	v_lshl_add_u64 v[4:5], s[10:11], 0, v[156:157]
	s_cbranch_scc1 .LBB0_922
	s_barrier

; __device__ __forceinline__ unsigned xb_ld(unsigned* p)              { return __hip_atomic_load(p, __ATOMIC_RELAXED, __HIP_MEMORY_SCOPE_AGENT); }
; __device__ __forceinline__ unsigned xb_add(unsigned* p, unsigned v) { return __hip_atomic_fetch_add(p, v, __ATOMIC_RELAXED, __HIP_MEMORY_SCOPE_AGENT); }
; #define XB_SPIN(cond, bar) do { unsigned _sp = 0; while (cond) { __builtin_amdgcn_s_sleep(1); \
;     if ((++_sp & 255u) == 0u) { if (xb_ld(&(bar)[XB_TMO])) break; if (_sp > XB_SPIN_CAP) { atomicAdd(&(bar)[XB_TMO], 1u); break; } } } } while (0)
; template <class Epi, class Sched, bool ALIGN_EPI = false, bool SP2 = false>
; __device__ __forceinline__ void gemm_phase(PG8_LAS unsigned char* lds, const Gemm g, const Sched& S, const Epi& E) {
;     int tid_l = threadIdx.x; asm volatile("" : "+v"(tid_l));
;     const int tid = tid_l, wid = __builtin_amdgcn_readfirstlane(tid >> 6), lane = tid & 63, wr = wid >> 2, wc = wid & 3, fr = lane & 15, fq = lane >> 4;
;     const int K = g.K, nt = K / BK;
;     unsigned voffA[2], voffB[2];
; #pragma unroll
;     for (int i = 0; i < 2; ++i) { int R, C; stage_rc(tid * 16 + i * 8192, R, C); const int Rb = Epi::PERM ? ((R & ~31) + perm32(R & 31)) : R;
;         voffA[i] = (unsigned)(R * K + C) * 2u; voffB[i] = (unsigned)(Rb * K + C) * 2u; }
;     const size_t kstep = (size_t)(BK * 2);
;     const size_t hstep = (size_t)HALF * K * 2;
;     const size_t tstep = 2 * hstep;
;     const unsigned ldsw = (unsigned)wid * 1024u;
;     const int aoff = lds_byte(wr * 64 + fr, fq * 8), boff = lds_byte(wc * 32 + fr, fq * 8);
; __device__ __forceinline__ void xcc_local_barrier(unsigned* bar, unsigned x, unsigned nloc) {
;     asm volatile("s_waitcnt vmcnt(0)" ::: "memory");
;     __syncthreads();
;     if (threadIdx.x == 0) {
;         __builtin_amdgcn_s_waitcnt(0);
;         const unsigned old = xb_add(&bar[LB_SUB(x)], 1u);
;         const unsigned gen = old / nloc;
;         if (old + 1u == (gen + 1u) * nloc) xb_add(&bar[LB_GEN(x)], 1u);
;         else XB_SPIN(xb_ld(&bar[LB_GEN(x)]) == gen, bar);
;         __builtin_amdgcn_fence(__ATOMIC_ACQUIRE, "agent");
;         asm volatile("s_waitcnt vmcnt(0)" ::: "memory");
;     }
;     __syncthreads();
.LBB0_1024:
	s_or_b64 exec, exec, s[2:3]
.LBB0_1025:
	s_mul_i32 s3, s78, 0x2c00000
	v_readlane_b32 s6, v249, 1
	s_add_u32 s46, s6, s3
	v_readlane_b32 s6, v250, 10
	s_mul_hi_u32 s2, s78, 0x2c00000
	v_readlane_b32 s3, v249, 2
	v_readlane_b32 s7, v250, 11
	s_addc_u32 s47, s3, s2
	s_mov_b64 s[2:3], -1
	s_and_b64 vcc, exec, s[6:7]
	s_waitcnt lgkmcnt(0)
	s_cbranch_vccz .LBB0_1043
	v_readlane_b32 s2, v248, 23
	v_mov_b32_e32 v10, v204
	v_readlane_b32 s3, v248, 24
	s_andn2_b64 vcc, exec, s[2:3]
	v_readfirstlane_b32 s2, v10
	s_cbranch_vccnz .LBB0_1042
	v_lshlrev_b32_e32 v1, 4, v10
	v_add_u32_e32 v0, 0x2000, v1
	v_ashrrev_i32_e32 v3, 31, v0
	v_lshrrev_b32_e32 v3, 22, v3
	v_add_u32_e32 v3, v0, v3
	v_ashrrev_i32_e32 v4, 10, v3
	v_mul_i32_i24_e32 v3, 0x400, v4
	v_sub_u32_e32 v0, v0, v3
	v_lshrrev_b32_e32 v3, 4, v0
	v_bitop3_b32 v0, v3, v0, 32 bitop3:0x6c
	v_ashrrev_i32_e32 v3, 31, v0
	v_lshrrev_b32_e32 v3, 26, v3
	v_add_u32_e32 v3, v0, v3
	v_lshlrev_b32_e32 v6, 3, v4
	v_ashrrev_i32_e32 v5, 6, v3
	v_and_b32_e32 v6, -16, v6
	v_add_u32_e32 v7, v5, v6
	v_and_b32_e32 v6, 3, v5
	s_mov_b32 s6, 0xfffe0
	v_lshrrev_b32_e32 v8, 2, v7
	v_lshlrev_b32_e32 v9, 1, v7
	v_and_b32_e32 v3, 0xc0, v3
	v_and_or_b32 v6, v7, s6, v6
	v_and_b32_e32 v8, 4, v8
	v_and_b32_e32 v9, 24, v9
	v_sub_u32_e32 v0, v0, v3
	v_or3_b32 v8, v6, v8, v9
	v_lshlrev_b32_e32 v6, 5, v4
	v_ashrrev_i16_sdwa v0, v207, sext(v0) dst_sel:DWORD dst_unused:UNUSED_PAD src0_sel:DWORD src1_sel:BYTE_0
	v_and_b32_e32 v9, 32, v6
	v_bfe_i32 v6, v0, 0, 16
	v_add_lshl_u32 v3, v9, v6, 1
	v_lshl_add_u32 v0, v8, 12, v3
	v_lshl_add_u32 v132, v7, 12, v3
	v_bfe_i32 v3, v10, 27, 1
	v_lshrrev_b32_e32 v3, 22, v3
	v_add_u32_e32 v3, v1, v3
	v_and_b32_e32 v3, 0xfffffc00, v3
	v_sub_u32_e32 v1, v1, v3
	v_lshrrev_b32_e32 v3, 4, v1
	v_ashrrev_i32_e32 v8, 31, v10
	v_bitop3_b32 v1, v3, v1, 32 bitop3:0x6c
	v_lshrrev_b32_e32 v8, 26, v8
	v_ashrrev_i32_e32 v3, 31, v1
	v_add_u32_e32 v8, v10, v8
	v_lshrrev_b32_e32 v3, 26, v3
	v_ashrrev_i32_e32 v8, 6, v8
	v_add_u32_e32 v3, v1, v3
	v_lshlrev_b32_e32 v9, 3, v8
	v_ashrrev_i32_e32 v7, 6, v3
	v_and_b32_e32 v9, -16, v9
	v_add_u32_e32 v11, v7, v9
	v_and_b32_e32 v9, 3, v7
	v_lshrrev_b32_e32 v12, 2, v11
	v_lshlrev_b32_e32 v13, 1, v11
	v_and_b32_e32 v3, 0xc0, v3
	s_ashr_i32 s3, s2, 6
	v_and_or_b32 v9, v11, s6, v9
	v_and_b32_e32 v12, 4, v12
	v_and_b32_e32 v13, 24, v13
	v_sub_u32_e32 v1, v1, v3
	s_ashr_i32 s8, s2, 8
	s_lshl_b32 s48, s3, 10
	v_or3_b32 v12, v9, v12, v13
	v_lshlrev_b32_e32 v9, 5, v8
	v_ashrrev_i16_sdwa v1, v207, sext(v1) dst_sel:DWORD dst_unused:UNUSED_PAD src0_sel:DWORD src1_sel:BYTE_0
	v_readlane_b32 s6, v248, 39
	v_and_b32_e32 v13, 32, v9
	v_bfe_i32 v9, v1, 0, 16
	v_readlane_b32 s7, v248, 40
	s_add_u32 s42, s46, s6
	v_add_lshl_u32 v1, v13, v9, 1
	s_addc_u32 s43, s47, s7
	s_add_i32 s49, s48, 0
	v_lshl_add_u32 v134, v12, 12, v1
	s_add_i32 m0, s49, 0x10000
	v_lshl_add_u32 v136, v11, 12, v1
	global_load_lds_dwordx4 v134, s[42:43]
	s_add_i32 m0, s49, 0x12000
	s_add_u32 s6, s42, 0x80000
	global_load_lds_dwordx4 v0, s[42:43]
	s_addc_u32 s7, s43, 0
	s_add_i32 m0, s49, 0x14000
	s_add_i32 s50, s49, 0x2000
	global_load_lds_dwordx4 v134, s[6:7]
	s_add_i32 m0, s49, 0x16000
	s_add_i32 s51, s49, 0x4000
	global_load_lds_dwordx4 v0, s[6:7]
	v_readlane_b32 s6, v248, 45
	s_mov_b32 m0, s49
	v_readlane_b32 s7, v248, 46
	s_add_i32 s52, s49, 0x6000
	s_cmp_eq_u32 s8, 1
	s_nop 2
	global_load_lds_dwordx4 v136, s[6:7]
	s_mov_b32 m0, s50
	s_nop 0
	global_load_lds_dwordx4 v132, s[6:7]
	v_readlane_b32 s6, v248, 47
	s_mov_b32 m0, s51
	v_readlane_b32 s7, v248, 48
	s_nop 4
	global_load_lds_dwordx4 v136, s[6:7]
	s_mov_b32 m0, s52
	s_nop 0
	global_load_lds_dwordx4 v132, s[6:7]
	s_cselect_b64 s[6:7], -1, 0
	s_cmp_lg_u32 s8, 1
	s_cbranch_scc1 .LBB0_1029
	s_barrier

; __device__ __forceinline__ float ss_get(const ss_t* p) { const ss_t v = *p; return (float)(unsigned)(v >> 32) + (float)(unsigned)v * 2.3283064365386963e-10f; }
;     __device__ __forceinline__ void operator()(const f32x4 (&acc)[2][2][4][2], const Unit& u, int wr, int wc, int fr, int fq) const {
;     ...
;             for (int m = 0; m < 4; ++m) { const int row = row0 + ai * HALF + m * 16; bf16_t* rowp = O + (size_t)row * ldc + col0;
;                 const float rs = 1.0f / sqrtf(ss_get(ssq + row) * (1.0f / 2048.f) + 1e-6f);
; template <class Epi, class Sched, bool ALIGN_EPI = false, bool SP2 = false>
; __device__ __forceinline__ void gemm_phase(PG8_LAS unsigned char* lds, const Gemm g, const Sched& S, const Epi& E) {
;     int tid_l = threadIdx.x; asm volatile("" : "+v"(tid_l));
;     const int tid = tid_l, wid = __builtin_amdgcn_readfirstlane(tid >> 6), lane = tid & 63, wr = wid >> 2, wc = wid & 3, fr = lane & 15, fq = lane >> 4;
;     const int K = g.K, nt = K / BK;
;     unsigned voffA[2], voffB[2];
; #pragma unroll
;     for (int i = 0; i < 2; ++i) { int R, C; stage_rc(tid * 16 + i * 8192, R, C); const int Rb = Epi::PERM ? ((R & ~31) + perm32(R & 31)) : R;
;         voffA[i] = (unsigned)(R * K + C) * 2u; voffB[i] = (unsigned)(Rb * K + C) * 2u; }
;     const size_t kstep = (size_t)(BK * 2);
;     const size_t hstep = (size_t)HALF * K * 2;
;     const size_t tstep = 2 * hstep;
;     const unsigned ldsw = (unsigned)wid * 1024u;
;     const int aoff = lds_byte(wr * 64 + fr, fq * 8), boff = lds_byte(wc * 32 + fr, fq * 8);
.LBB0_1043:
	s_andn2_b64 vcc, exec, s[2:3]
	s_cbranch_vccnz .Leb_p4_stub
	v_readlane_b32 s2, v248, 27
	v_mov_b32_e32 v3, v204
	v_readlane_b32 s3, v248, 28
	s_andn2_b64 vcc, exec, s[2:3]
	v_readfirstlane_b32 s2, v3
	s_cbranch_vccnz .Leb_p4_stub
	v_readlane_b32 s100, v250, 59
	v_bfe_u32 v252, v204, 8, 1
	v_and_b32_e32 v253, 15, v204
	v_lshl_or_b32 v252, v252, 6, v253
	v_add_u32_e32 v252, s100, v252
	v_mov_b32_e32 v253, 0
	v_lshl_add_u64 v[252:253], v[252:253], 3, s[4:5]
	v_lshlrev_b32_e32 v1, 4, v3
	v_add_u32_e32 v0, 0x2000, v1
	v_ashrrev_i32_e32 v4, 31, v0
	v_lshrrev_b32_e32 v4, 22, v4
	v_add_u32_e32 v4, v0, v4
	v_ashrrev_i32_e32 v8, 10, v4
	v_mul_i32_i24_e32 v4, 0x400, v8
	v_sub_u32_e32 v0, v0, v4
	v_lshrrev_b32_e32 v4, 4, v0
	v_bitop3_b32 v0, v4, v0, 32 bitop3:0x6c
	v_ashrrev_i32_e32 v4, 31, v0
	v_lshrrev_b32_e32 v4, 26, v4
	v_add_u32_e32 v4, v0, v4
	v_lshlrev_b32_e32 v5, 3, v8
	v_ashrrev_i32_e32 v9, 6, v4
	v_and_b32_e32 v5, -16, v5
	v_add_u32_e32 v5, v9, v5
	v_and_b32_e32 v6, 3, v9
	s_mov_b32 s6, 0xfffe0
	v_lshrrev_b32_e32 v7, 2, v5
	v_lshlrev_b32_e32 v10, 1, v5
	v_and_b32_e32 v4, 0xc0, v4
	v_and_or_b32 v6, v5, s6, v6
	v_and_b32_e32 v7, 4, v7
	v_and_b32_e32 v10, 24, v10
	v_sub_u32_e32 v0, v0, v4
	v_or3_b32 v6, v6, v7, v10
	v_lshlrev_b32_e32 v7, 5, v8
	v_ashrrev_i16_sdwa v0, v207, sext(v0) dst_sel:DWORD dst_unused:UNUSED_PAD src0_sel:DWORD src1_sel:BYTE_0
	v_and_b32_e32 v7, 32, v7
	v_bfe_i32 v10, v0, 0, 16
	v_add_lshl_u32 v4, v7, v10, 1
	v_lshl_add_u32 v0, v6, 12, v4
	v_lshl_add_u32 v132, v5, 12, v4
	v_bfe_i32 v4, v3, 27, 1
	v_lshrrev_b32_e32 v4, 22, v4
	v_add_u32_e32 v4, v1, v4
	v_and_b32_e32 v4, 0xfffffc00, v4
	v_sub_u32_e32 v1, v1, v4
	v_lshrrev_b32_e32 v4, 4, v1
	v_ashrrev_i32_e32 v5, 31, v3
	v_bitop3_b32 v1, v4, v1, 32 bitop3:0x6c
	v_lshrrev_b32_e32 v5, 26, v5
	v_ashrrev_i32_e32 v4, 31, v1
	v_add_u32_e32 v5, v3, v5
	v_lshrrev_b32_e32 v4, 26, v4
	v_ashrrev_i32_e32 v12, 6, v5
	v_add_u32_e32 v4, v1, v4
	v_lshlrev_b32_e32 v5, 3, v12
	v_ashrrev_i32_e32 v11, 6, v4
	v_and_b32_e32 v5, -16, v5
	v_add_u32_e32 v5, v11, v5
	v_and_b32_e32 v6, 3, v11
	v_lshrrev_b32_e32 v7, 2, v5
	v_lshlrev_b32_e32 v13, 1, v5
	v_and_b32_e32 v4, 0xc0, v4
	s_ashr_i32 s3, s2, 6
	v_and_or_b32 v6, v5, s6, v6
	v_and_b32_e32 v7, 4, v7
	v_and_b32_e32 v13, 24, v13
	v_sub_u32_e32 v1, v1, v4
	s_ashr_i32 s10, s2, 8
	s_lshl_b32 s42, s3, 10
	v_or3_b32 v6, v6, v7, v13
	v_lshlrev_b32_e32 v7, 5, v12
	v_ashrrev_i16_sdwa v1, v207, sext(v1) dst_sel:DWORD dst_unused:UNUSED_PAD src0_sel:DWORD src1_sel:BYTE_0
	v_readlane_b32 s6, v248, 31
	v_and_b32_e32 v7, 32, v7
	v_bfe_i32 v13, v1, 0, 16
	v_readlane_b32 s7, v248, 32
	s_add_u32 s6, s46, s6
	v_add_lshl_u32 v1, v7, v13, 1
	s_addc_u32 s7, s47, s7
	s_add_i32 s43, s42, 0
	v_lshl_add_u32 v134, v6, 12, v1
	s_add_i32 m0, s43, 0x10000
	v_lshl_add_u32 v136, v5, 12, v1
	s_barrier
	global_load_dwordx2 v[172:173], v[252:253], off
	global_load_dwordx2 v[174:175], v[252:253], off offset:128
	global_load_dwordx2 v[176:177], v[252:253], off offset:256
	global_load_dwordx2 v[178:179], v[252:253], off offset:384
	global_load_dwordx2 v[180:181], v[252:253], off offset:1024
	global_load_dwordx2 v[182:183], v[252:253], off offset:1152
	global_load_dwordx2 v[184:185], v[252:253], off offset:1280
	global_load_dwordx2 v[186:187], v[252:253], off offset:1408
	global_load_lds_dwordx4 v134, s[6:7]
	s_add_i32 m0, s43, 0x12000
	s_add_u32 s8, s6, 0x80000
	global_load_lds_dwordx4 v0, s[6:7]
	s_addc_u32 s9, s7, 0
	s_add_i32 m0, s43, 0x14000
	s_add_i32 s44, s43, 0x2000
	global_load_lds_dwordx4 v134, s[8:9]
	s_add_i32 m0, s43, 0x16000
	s_add_i32 s45, s43, 0x4000
	global_load_lds_dwordx4 v0, s[8:9]
	s_mov_b32 m0, s43
	v_readlane_b32 s8, v250, 57
	global_load_lds_dwordx4 v136, s[0:1]
	s_mov_b32 m0, s44
	v_readlane_b32 s9, v250, 58
	global_load_lds_dwordx4 v132, s[0:1]
	s_mov_b32 m0, s45
	s_add_i32 s48, s43, 0x6000
	v_mov_b32_e32 v135, v2
	s_nop 0
	global_load_lds_dwordx4 v136, s[8:9]
	s_mov_b32 m0, s48
	v_mov_b32_e32 v1, v2
	global_load_lds_dwordx4 v132, s[8:9]
	s_cmp_eq_u32 s10, 1
	v_lshl_add_u64 v[4:5], s[6:7], 0, v[134:135]
	s_cselect_b64 s[8:9], -1, 0
	s_cmp_lg_u32 s10, 1
	v_lshl_add_u64 v[6:7], s[6:7], 0, v[0:1]
	s_cbranch_scc1 .LBB0_1047
	s_barrier

; template <class Epi, class Sched, bool ALIGN_EPI = false, bool SP2 = false>
; __device__ __forceinline__ void gemm_phase(PG8_LAS unsigned char* lds, const Gemm g, const Sched& S, const Epi& E) {
;     int tid_l = threadIdx.x; asm volatile("" : "+v"(tid_l));
;     const int tid = tid_l, wid = __builtin_amdgcn_readfirstlane(tid >> 6), lane = tid & 63, wr = wid >> 2, wc = wid & 3, fr = lane & 15, fq = lane >> 4;
;     const int K = g.K, nt = K / BK;
;     unsigned voffA[2], voffB[2];
; #pragma unroll
;     for (int i = 0; i < 2; ++i) { int R, C; stage_rc(tid * 16 + i * 8192, R, C); const int Rb = Epi::PERM ? ((R & ~31) + perm32(R & 31)) : R;
;         voffA[i] = (unsigned)(R * K + C) * 2u; voffB[i] = (unsigned)(Rb * K + C) * 2u; }
;     const size_t kstep = (size_t)(BK * 2);
;     const size_t hstep = (size_t)HALF * K * 2;
;     const size_t tstep = 2 * hstep;
;     const unsigned ldsw = (unsigned)wid * 1024u;
;     const int aoff = lds_byte(wr * 64 + fr, fq * 8), boff = lds_byte(wc * 32 + fr, fq * 8);
; __global__ void __launch_bounds__(NWAVES * 64, 2) fwd_kernel(Args A) {
;     ...
;         { pg8::Gemm g{ACT, (const bf16*)(ws + WS_WDN + l * SZ_WDN), SEQ, DM, DFF};
;           const bool more = l + 1 < DEPTH;
;           pg8::EpiResid<false> E{more ? nullptr : X, DM, XB, SS + (size_t)(SS_Q1 + (more ? l + 1 : 0)) * SEQ, nullptr, nullptr};
;           if (G == 256) { pg8::OrderTok S{vc, DM / 256, 0}; pg8::gemm_phase<pg8::EpiResid<false>, pg8::OrderTok, true, true>(ldsl, g, S, E); }
;           else { pg8::StaticOrder S; S.init(SEQ, DM, G, bx); pg8::gemm_phase<pg8::EpiResid<false>, pg8::StaticOrder, true, true>(ldsl, g, S, E); } }
.LBB0_1146:
	s_or_b64 exec, exec, s[2:3]
	s_mul_i32 s3, s78, 0x1600000
	v_readlane_b32 s4, v250, 63
	s_mul_hi_u32 s2, s78, 0x1600000
	s_add_u32 s55, s4, s3
	v_readlane_b32 s3, v249, 0
	s_addc_u32 s56, s3, s2
	s_add_i32 s54, s78, 1
	s_cmp_eq_u32 s78, 3
	s_cselect_b64 s[2:3], -1, 0
	s_cmp_lg_u32 s78, 3
	v_readlane_b32 s8, v250, 1
	s_cselect_b64 s[4:5], -1, 0
	s_and_b64 s[6:7], s[2:3], exec
	v_readlane_b32 s10, v250, 3
	v_readlane_b32 s11, v250, 4
	s_cselect_b32 s7, s11, 0
	s_cselect_b32 s6, s10, 0
	s_lshl_b32 s8, s54, 13
	s_and_b64 s[2:3], s[2:3], exec
	s_cselect_b32 s76, 0, s8
	s_lshl_b64 s[2:3], s[76:77], 3
	v_readlane_b32 s10, v250, 10
	v_readlane_b32 s9, v250, 2
	s_add_u32 s8, s80, s2
	v_readlane_b32 s2, v250, 46
	v_readlane_b32 s11, v250, 11
	s_addc_u32 s9, s2, s3
	s_mov_b64 s[2:3], -1
	s_and_b64 vcc, exec, s[10:11]
	s_waitcnt lgkmcnt(0)
	s_cbranch_vccz .LBB0_1268
	s_barrier
	v_readlane_b32 s2, v247, 31
	v_mov_b32_e32 v16, v204
	v_readlane_b32 s3, v247, 32
	s_and_b64 vcc, exec, s[2:3]
	v_readfirstlane_b32 s2, v16
	s_cbranch_vccnz .LBB0_1267
	v_lshlrev_b32_e32 v1, 4, v16
	v_add_u32_e32 v0, 0x2000, v1
	v_ashrrev_i32_e32 v3, 31, v0
	v_lshrrev_b32_e32 v3, 22, v3
	v_add_u32_e32 v3, v0, v3
	v_ashrrev_i32_e32 v8, 10, v3
	v_mul_i32_i24_e32 v3, 0x400, v8
	v_sub_u32_e32 v0, v0, v3
	v_lshrrev_b32_e32 v3, 4, v0
	v_bitop3_b32 v0, v3, v0, 32 bitop3:0x6c
	v_ashrrev_i32_e32 v3, 31, v0
	v_lshrrev_b32_e32 v3, 26, v3
	v_add_u32_e32 v3, v0, v3
	v_lshlrev_b32_e32 v4, 3, v8
	v_ashrrev_i32_e32 v9, 6, v3
	v_and_b32_e32 v4, -16, v4
	v_add_u32_e32 v4, v9, v4
	v_and_b32_e32 v5, 3, v9
	s_mov_b32 s11, 0x7fffe0
	v_lshrrev_b32_e32 v6, 2, v4
	v_lshlrev_b32_e32 v7, 1, v4
	v_and_b32_e32 v3, 0xc0, v3
	v_and_or_b32 v5, v4, s11, v5
	v_and_b32_e32 v6, 4, v6
	v_and_b32_e32 v7, 24, v7
	v_sub_u32_e32 v0, v0, v3
	v_or3_b32 v5, v5, v6, v7
	v_lshlrev_b32_e32 v6, 5, v8
	v_ashrrev_i16_sdwa v0, v207, sext(v0) dst_sel:DWORD dst_unused:UNUSED_PAD src0_sel:DWORD src1_sel:BYTE_0
	v_and_b32_e32 v10, 32, v6
	v_bfe_i32 v11, v0, 0, 16
	s_movk_i32 s10, 0x1600
	v_mul_u32_u24_e32 v5, 0x1600, v5
	v_add_u32_e32 v3, v10, v11
	v_mul_lo_u32 v4, v4, s10
	v_add_lshl_u32 v0, v5, v3, 1
	v_add_lshl_u32 v172, v3, v4, 1
	v_bfe_i32 v3, v16, 27, 1
	v_lshrrev_b32_e32 v3, 22, v3
	v_add_u32_e32 v3, v1, v3
	v_and_b32_e32 v3, 0xfffffc00, v3
	v_sub_u32_e32 v1, v1, v3
	v_lshrrev_b32_e32 v3, 4, v1
	v_ashrrev_i32_e32 v4, 31, v16
	v_bitop3_b32 v1, v3, v1, 32 bitop3:0x6c
	v_lshrrev_b32_e32 v4, 26, v4
	v_ashrrev_i32_e32 v3, 31, v1
	v_add_u32_e32 v4, v16, v4
	v_lshrrev_b32_e32 v3, 26, v3
	v_ashrrev_i32_e32 v13, 6, v4
	v_add_u32_e32 v3, v1, v3
	v_lshlrev_b32_e32 v4, 3, v13
	v_ashrrev_i32_e32 v12, 6, v3
	v_and_b32_e32 v4, -16, v4
	v_add_u32_e32 v4, v12, v4
	v_and_b32_e32 v5, 3, v12
	v_lshrrev_b32_e32 v6, 2, v4
	v_lshlrev_b32_e32 v7, 1, v4
	v_and_b32_e32 v3, 0xc0, v3
	s_ashr_i32 s3, s2, 6
	v_and_or_b32 v5, v4, s11, v5
	v_and_b32_e32 v6, 4, v6
	v_and_b32_e32 v7, 24, v7
	v_sub_u32_e32 v1, v1, v3
	v_readlane_b32 s11, v248, 42
	s_ashr_i32 s12, s2, 8
	s_lshl_b32 s57, s3, 10
	v_or3_b32 v5, v5, v6, v7
	v_lshlrev_b32_e32 v6, 5, v13
	v_ashrrev_i16_sdwa v1, v207, sext(v1) dst_sel:DWORD dst_unused:UNUSED_PAD src0_sel:DWORD src1_sel:BYTE_0
	v_mul_lo_u32 v3, v4, s10
	s_mul_i32 s10, s11, 0x2c0000
	v_and_b32_e32 v14, 32, v6
	v_bfe_i32 v15, v1, 0, 16
	s_add_u32 s50, s55, s10
	s_mul_hi_i32 s10, s11, 0x2c0000
	v_mul_u32_u24_e32 v5, 0x1600, v5
	v_add_u32_e32 v1, v14, v15
	s_addc_u32 s51, s56, s10
	s_add_i32 s58, s57, 0
	v_add_lshl_u32 v174, v5, v1, 1
	s_add_i32 m0, s58, 0x10000
	v_add_lshl_u32 v176, v1, v3, 1
	global_load_lds_dwordx4 v174, s[50:51]
	s_add_i32 m0, s58, 0x12000
	s_add_u32 s10, s50, 0x160000
	global_load_lds_dwordx4 v0, s[50:51]
	s_addc_u32 s11, s51, 0
	s_add_i32 m0, s58, 0x14000
	s_add_i32 s59, s58, 0x2000
	global_load_lds_dwordx4 v174, s[10:11]
	s_add_i32 m0, s58, 0x16000
	s_add_i32 s60, s58, 0x4000
	global_load_lds_dwordx4 v0, s[10:11]
	v_readlane_b32 s10, v247, 6
	s_mov_b32 m0, s58
	v_readlane_b32 s11, v247, 7
	s_add_i32 s61, s58, 0x6000
	v_mov_b32_e32 v175, v2
	v_mov_b32_e32 v1, v2
	s_cmp_eq_u32 s12, 1
	v_lshl_add_u64 v[4:5], s[50:51], 0, v[174:175]
	global_load_lds_dwordx4 v176, s[10:11]
	s_mov_b32 m0, s59
	v_lshl_add_u64 v[6:7], s[50:51], 0, v[0:1]
	global_load_lds_dwordx4 v172, s[10:11]
	v_readlane_b32 s10, v247, 8
	s_mov_b32 m0, s60
	v_readlane_b32 s11, v247, 9
	s_nop 4
	global_load_lds_dwordx4 v176, s[10:11]
	s_mov_b32 m0, s61
	s_nop 0
	global_load_lds_dwordx4 v172, s[10:11]
	s_cselect_b64 s[10:11], -1, 0
	s_cmp_lg_u32 s12, 1
	s_cbranch_scc1 .LBB0_1150
	s_barrier

; #define PG8_STAGE(bufoff, gbase, voff) do { _Pragma("unroll") for (int _i = 0; _i < 2; ++_i) \
;         __builtin_amdgcn_global_load_lds((const unsigned*)((const char*)(gbase) + (voff)[_i]), (PG8_LAS unsigned*)(lds + (bufoff) + ldsw + _i * 8192), 16, 0, 0); } while (0)
; #define PG8_WAIT_V(n) asm volatile("s_waitcnt vmcnt(" #n ")" ::: "memory")
; #define PG8_BAR __builtin_amdgcn_s_barrier()
; template <class Epi, class Sched, bool ALIGN_EPI = false, bool SP2 = false>
; __device__ __forceinline__ void gemm_phase(PG8_LAS unsigned char* lds, const Gemm g, const Sched& S, const Epi& E) {
;     int tid_l = threadIdx.x; asm volatile("" : "+v"(tid_l));
;     const int tid = tid_l, wid = __builtin_amdgcn_readfirstlane(tid >> 6), lane = tid & 63, wr = wid >> 2, wc = wid & 3, fr = lane & 15, fq = lane >> 4;
;     const int K = g.K, nt = K / BK;
;     unsigned voffA[2], voffB[2];
; #pragma unroll
;     for (int i = 0; i < 2; ++i) { int R, C; stage_rc(tid * 16 + i * 8192, R, C); const int Rb = Epi::PERM ? ((R & ~31) + perm32(R & 31)) : R;
;         voffA[i] = (unsigned)(R * K + C) * 2u; voffB[i] = (unsigned)(Rb * K + C) * 2u; }
;     const size_t kstep = (size_t)(BK * 2);
;     const size_t hstep = (size_t)HALF * K * 2;
;     const size_t tstep = 2 * hstep;
;     const unsigned ldsw = (unsigned)wid * 1024u;
;     const int aoff = lds_byte(wr * 64 + fr, fq * 8), boff = lds_byte(wc * 32 + fr, fq * 8);
;     ...
;     const char* cA = (const char*)g.A + (size_t)cur.pm * tstep; const char* cB = (const char*)g.Bt + (size_t)cur.pn * tstep;
;     S.a_ready(cur);
;     if constexpr (SP2) {
;         PG8_STAGE(PG8_SB(0, 0), cB, voffB); PG8_STAGE(PG8_SB(0, 1), cB + hstep, voffB); PG8_STAGE(PG8_SA(0, 0), cA, voffA); PG8_STAGE(PG8_SA(0, 1), cA + hstep, voffA);
;         if (wr == 1) PG8_BAR;
;         PG8_WAIT_V(2); PG8_BAR;
;         PG8_STAGE(PG8_SB(1, 0), cB + kstep, voffB); PG8_STAGE(PG8_SA(1, 0), cA + kstep, voffA); PG8_STAGE(PG8_SB(1, 1), cB + hstep + kstep, voffB);
;         PG8_WAIT_V(6); PG8_BAR;
;     } else {
;         PG8_STAGE(PG8_SB(0, 0), cB, voffB); PG8_STAGE(PG8_SA(0, 0), cA, voffA); PG8_STAGE(PG8_SB(0, 1), cB + hstep, voffB); PG8_STAGE(PG8_SA(0, 1), cA + hstep, voffA);
.LBB0_1268:
	s_andn2_b64 vcc, exec, s[2:3]
	s_cbranch_vccnz .Leb_p5_stub
	v_mov_b32_e32 v3, v204
	s_and_b64 vcc, exec, s[38:39]
	v_readfirstlane_b32 s12, v3
	s_cbranch_vccnz .Leb_p5_stub
	v_lshlrev_b32_e32 v1, 4, v3
	v_add_u32_e32 v0, 0x2000, v1
	v_ashrrev_i32_e32 v4, 31, v0
	v_lshrrev_b32_e32 v4, 22, v4
	v_add_u32_e32 v4, v0, v4
	v_ashrrev_i32_e32 v8, 10, v4
	v_mul_i32_i24_e32 v4, 0x400, v8
	v_sub_u32_e32 v0, v0, v4
	v_lshrrev_b32_e32 v4, 4, v0
	v_bitop3_b32 v0, v4, v0, 32 bitop3:0x6c
	v_ashrrev_i32_e32 v4, 31, v0
	v_lshrrev_b32_e32 v4, 26, v4
	v_add_u32_e32 v4, v0, v4
	s_waitcnt lgkmcnt(0)
	v_lshlrev_b32_e32 v5, 3, v8
	v_ashrrev_i32_e32 v9, 6, v4
	v_and_b32_e32 v5, -16, v5
	v_add_u32_e32 v5, v9, v5
	v_and_b32_e32 v6, 3, v9
	s_mov_b32 s3, 0x7fffe0
	v_lshrrev_b32_e32 v7, 2, v5
	v_lshlrev_b32_e32 v10, 1, v5
	v_and_b32_e32 v4, 0xc0, v4
	v_and_or_b32 v6, v5, s3, v6
	v_and_b32_e32 v7, 4, v7
	v_and_b32_e32 v10, 24, v10
	v_sub_u32_e32 v0, v0, v4
	v_or3_b32 v6, v6, v7, v10
	v_lshlrev_b32_e32 v7, 5, v8
	v_ashrrev_i16_sdwa v0, v207, sext(v0) dst_sel:DWORD dst_unused:UNUSED_PAD src0_sel:DWORD src1_sel:BYTE_0
	v_and_b32_e32 v10, 32, v7
	v_bfe_i32 v11, v0, 0, 16
	s_movk_i32 s2, 0x1600
	v_mul_u32_u24_e32 v6, 0x1600, v6
	v_add_u32_e32 v4, v10, v11
	v_mul_lo_u32 v5, v5, s2
	v_add_lshl_u32 v0, v6, v4, 1
	v_add_lshl_u32 v172, v4, v5, 1
	v_bfe_i32 v4, v3, 27, 1
	v_lshrrev_b32_e32 v4, 22, v4
	v_add_u32_e32 v4, v1, v4
	v_and_b32_e32 v4, 0xfffffc00, v4
	v_sub_u32_e32 v1, v1, v4
	v_lshrrev_b32_e32 v4, 4, v1
	v_ashrrev_i32_e32 v5, 31, v3
	v_bitop3_b32 v1, v4, v1, 32 bitop3:0x6c
	v_lshrrev_b32_e32 v5, 26, v5
	v_ashrrev_i32_e32 v4, 31, v1
	v_add_u32_e32 v5, v3, v5
	v_lshrrev_b32_e32 v4, 26, v4
	v_ashrrev_i32_e32 v13, 6, v5
	v_add_u32_e32 v4, v1, v4
	v_lshlrev_b32_e32 v5, 3, v13
	v_ashrrev_i32_e32 v12, 6, v4
	v_and_b32_e32 v5, -16, v5
	v_add_u32_e32 v5, v12, v5
	v_and_b32_e32 v6, 3, v12
	v_lshrrev_b32_e32 v7, 2, v5
	v_lshlrev_b32_e32 v14, 1, v5
	v_and_b32_e32 v4, 0xc0, v4
	s_ashr_i32 s13, s12, 6
	v_and_or_b32 v6, v5, s3, v6
	v_and_b32_e32 v7, 4, v7
	v_and_b32_e32 v14, 24, v14
	v_sub_u32_e32 v1, v1, v4
	v_mul_lo_u32 v4, v5, s2
	v_readlane_b32 s2, v248, 25
	s_ashr_i32 s14, s12, 8
	s_lshl_b32 s48, s13, 10
	v_or3_b32 v6, v6, v7, v14
	v_lshlrev_b32_e32 v7, 5, v13
	v_ashrrev_i16_sdwa v1, v207, sext(v1) dst_sel:DWORD dst_unused:UNUSED_PAD src0_sel:DWORD src1_sel:BYTE_0
	v_readlane_b32 s3, v248, 26
	s_mov_b32 s10, s2
	s_mul_i32 s2, s2, 0x2c0000
	v_and_b32_e32 v14, 32, v7
	v_bfe_i32 v15, v1, 0, 16
	s_add_u32 s2, s55, s2
	s_mul_hi_i32 s3, s10, 0x2c0000
	v_mul_u32_u24_e32 v6, 0x1600, v6
	v_add_u32_e32 v1, v14, v15
	s_addc_u32 s3, s56, s3
	s_add_i32 s49, s48, 0
	v_add_lshl_u32 v174, v6, v1, 1
	s_add_i32 m0, s49, 0x10000
	v_add_lshl_u32 v176, v1, v4, 1
	s_barrier
	global_load_lds_dwordx4 v174, s[2:3]
	s_add_i32 m0, s49, 0x12000
	s_add_u32 s10, s2, 0x160000
	global_load_lds_dwordx4 v0, s[2:3]
	s_addc_u32 s11, s3, 0
	s_add_i32 m0, s49, 0x14000
	s_add_i32 s50, s49, 0x2000
	global_load_lds_dwordx4 v174, s[10:11]
	s_add_i32 m0, s49, 0x16000
	s_add_i32 s51, s49, 0x4000
	global_load_lds_dwordx4 v0, s[10:11]
	s_mov_b32 m0, s49
	v_readlane_b32 s10, v248, 36
	global_load_lds_dwordx4 v176, s[34:35]
	s_mov_b32 m0, s50
	v_readlane_b32 s11, v248, 37
	global_load_lds_dwordx4 v172, s[34:35]
	s_mov_b32 m0, s51
	s_add_i32 s52, s49, 0x6000
	v_mov_b32_e32 v175, v2
	s_nop 0
	global_load_lds_dwordx4 v176, s[10:11]
	s_mov_b32 m0, s52
	v_mov_b32_e32 v1, v2
	global_load_lds_dwordx4 v172, s[10:11]
	s_cmp_eq_u32 s14, 1
	v_lshl_add_u64 v[4:5], s[2:3], 0, v[174:175]
	s_cselect_b64 s[10:11], -1, 0
	s_cmp_lg_u32 s14, 1
	v_lshl_add_u64 v[6:7], s[2:3], 0, v[0:1]
	s_cbranch_scc1 .LBB0_1272
	s_barrier
